# grid barrier: the workgroup whose arrival brings its XCD count to half issues an early unwaited L2 writeback, so the leader's release fence finds less dirty data
# speedup vs baseline: 1.0052x; 1.0045x over previous
; DI unsigned xb_ld(unsigned* p)              { return __hip_atomic_load(p, __ATOMIC_RELAXED, __HIP_MEMORY_SCOPE_AGENT); }
; DI unsigned xb_add(unsigned* p, unsigned v) { return __hip_atomic_fetch_add(p, v, __ATOMIC_RELAXED, __HIP_MEMORY_SCOPE_AGENT); }
; #define XB_SPIN(cond, bar) do { unsigned _sp = 0; while (cond) { __builtin_amdgcn_s_sleep(1); \
;     if ((++_sp & 255u) == 0u) { if (xb_ld(&(bar)[XB_TMO])) break; if (_sp > XB_SPIN_CAP) { atomicAdd(&(bar)[XB_TMO], 1u); break; } } } } while (0)
; DI void xcd_barrier(const XcdBarrier& b, int tid) {
;     ...
;         const unsigned old = xb_add(&bar[XB_XSUB(b.x)], 1u);
;         const unsigned gen = old / nloc;
;         if (old + 1u == (gen + 1u) * nloc) {
;             __builtin_amdgcn_fence(__ATOMIC_RELEASE, "agent");
;             asm volatile("s_waitcnt vmcnt(0)" ::: "memory");
;             const unsigned og = xb_add(&bar[XB_TOP], 1u);
;             const unsigned tg = og / nx;
;             if (og + 1u == (tg + 1u) * nx) xb_add(&bar[XB_TOPGEN], 1u);
;             else XB_SPIN(xb_ld(&bar[XB_TOPGEN]) == tg, bar);
;             __builtin_amdgcn_fence(__ATOMIC_ACQUIRE, "agent");
;             xb_add(&bar[XB_XGEN(b.x)], 1u);
;             asm volatile("s_waitcnt vmcnt(0)" ::: "memory");
;         } else {
;             XB_SPIN(xb_ld(&bar[XB_XGEN(b.x)]) == gen, bar);
.LBB0_107:
	s_or_b64 exec, exec, s[4:5]
	v_cvt_f32_u32_e32 v4, v2
	s_waitcnt vmcnt(0)
	v_readfirstlane_b32 s2, v3
	v_sub_u32_e32 v3, 0, v2
	v_rcp_iflag_f32_e32 v4, v4
	v_add_u32_e32 v5, s2, v1
	v_mul_f32_e32 v4, 0x4f7ffffe, v4
	v_cvt_u32_f32_e32 v4, v4
	v_mul_lo_u32 v1, v3, v4
	v_mul_hi_u32 v1, v4, v1
	v_add_u32_e32 v1, v4, v1
	v_mul_hi_u32 v1, v5, v1
	v_mul_lo_u32 v3, v1, v2
	v_sub_u32_e32 v3, v5, v3
	v_add_u32_e32 v4, 1, v1
	v_cmp_ge_u32_e32 vcc, v3, v2
	s_nop 1
	v_cndmask_b32_e32 v1, v1, v4, vcc
	v_sub_u32_e32 v4, v3, v2
	v_cndmask_b32_e32 v3, v3, v4, vcc
	v_add_u32_e32 v4, 1, v1
	v_cmp_ge_u32_e32 vcc, v3, v2
	v_add_u32_e32 v3, 1, v5
	s_nop 0
	v_cndmask_b32_e32 v1, v1, v4, vcc
	v_mul_lo_u32 v4, v2, v1
	v_add_u32_e32 v2, v4, v2
	v_cmp_ne_u32_e32 vcc, v3, v2
	s_and_saveexec_b64 s[2:3], vcc
	s_xor_b64 s[4:5], exec, s[2:3]
	s_cbranch_execz .LBB0_121
	v_sub_u32_e32 v4, v2, v4
	v_lshrrev_b32_e32 v4, 1, v4
	v_sub_u32_e32 v4, v2, v4
	v_cmp_eq_u32_e32 vcc, v3, v4
	s_cbranch_vccz .Lbarwb_skip_0
	buffer_wbl2 sc1
.Lbarwb_skip_0:
	s_nop 0
	s_nop 0
	s_nop 0
	s_nop 0
	s_nop 0
	s_nop 0
	s_nop 0
	s_nop 0
	s_nop 0
	v_readlane_b32 s2, v254, 10
	s_waitcnt lgkmcnt(0)
	v_mov_b32_e32 v0, 0
	v_readlane_b32 s3, v254, 11
	s_nop 4
	global_load_dword v2, v0, s[2:3] sc1
	s_waitcnt vmcnt(0)
	v_cmp_eq_u32_e32 vcc, v2, v1
	s_and_saveexec_b64 s[6:7], vcc
	s_cbranch_execz .LBB0_120
	s_mov_b32 s2, 1
	s_mov_b64 s[8:9], 0
	s_branch .LBB0_111

; DI unsigned xb_ld(unsigned* p)              { return __hip_atomic_load(p, __ATOMIC_RELAXED, __HIP_MEMORY_SCOPE_AGENT); }
; DI unsigned xb_add(unsigned* p, unsigned v) { return __hip_atomic_fetch_add(p, v, __ATOMIC_RELAXED, __HIP_MEMORY_SCOPE_AGENT); }
; #define XB_SPIN(cond, bar) do { unsigned _sp = 0; while (cond) { __builtin_amdgcn_s_sleep(1); \
;     if ((++_sp & 255u) == 0u) { if (xb_ld(&(bar)[XB_TMO])) break; if (_sp > XB_SPIN_CAP) { atomicAdd(&(bar)[XB_TMO], 1u); break; } } } } while (0)
; DI void xcd_barrier(const XcdBarrier& b, int tid) {
;     ...
;         const unsigned old = xb_add(&bar[XB_XSUB(b.x)], 1u);
;         const unsigned gen = old / nloc;
;         if (old + 1u == (gen + 1u) * nloc) {
;             __builtin_amdgcn_fence(__ATOMIC_RELEASE, "agent");
;             asm volatile("s_waitcnt vmcnt(0)" ::: "memory");
;             const unsigned og = xb_add(&bar[XB_TOP], 1u);
;             const unsigned tg = og / nx;
;             if (og + 1u == (tg + 1u) * nx) xb_add(&bar[XB_TOPGEN], 1u);
;             else XB_SPIN(xb_ld(&bar[XB_TOPGEN]) == tg, bar);
;             __builtin_amdgcn_fence(__ATOMIC_ACQUIRE, "agent");
;             xb_add(&bar[XB_XGEN(b.x)], 1u);
;             asm volatile("s_waitcnt vmcnt(0)" ::: "memory");
;         } else {
;             XB_SPIN(xb_ld(&bar[XB_XGEN(b.x)]) == gen, bar);
.LBB0_342:
	s_or_b64 exec, exec, s[4:5]
	v_cvt_f32_u32_e32 v4, v2
	s_waitcnt vmcnt(0)
	v_readfirstlane_b32 s2, v3
	v_sub_u32_e32 v3, 0, v2
	v_rcp_iflag_f32_e32 v4, v4
	v_add_u32_e32 v5, s2, v1
	v_mul_f32_e32 v4, 0x4f7ffffe, v4
	v_cvt_u32_f32_e32 v4, v4
	v_mul_lo_u32 v1, v3, v4
	v_mul_hi_u32 v1, v4, v1
	v_add_u32_e32 v1, v4, v1
	v_mul_hi_u32 v1, v5, v1
	v_mul_lo_u32 v3, v1, v2
	v_sub_u32_e32 v3, v5, v3
	v_add_u32_e32 v4, 1, v1
	v_cmp_ge_u32_e32 vcc, v3, v2
	s_nop 1
	v_cndmask_b32_e32 v1, v1, v4, vcc
	v_sub_u32_e32 v4, v3, v2
	v_cndmask_b32_e32 v3, v3, v4, vcc
	v_add_u32_e32 v4, 1, v1
	v_cmp_ge_u32_e32 vcc, v3, v2
	v_add_u32_e32 v3, 1, v5
	s_nop 0
	v_cndmask_b32_e32 v1, v1, v4, vcc
	v_mul_lo_u32 v4, v2, v1
	v_add_u32_e32 v2, v4, v2
	v_cmp_ne_u32_e32 vcc, v3, v2
	s_and_saveexec_b64 s[4:5], vcc
	s_xor_b64 s[4:5], exec, s[4:5]
	s_cbranch_execz .LBB0_356
	v_sub_u32_e32 v4, v2, v4
	v_lshrrev_b32_e32 v4, 1, v4
	v_sub_u32_e32 v4, v2, v4
	v_cmp_eq_u32_e32 vcc, v3, v4
	s_cbranch_vccz .Lbarwb_skip_2
	buffer_wbl2 sc1
.Lbarwb_skip_2:
	s_nop 0
	s_nop 0
	s_nop 0
	s_nop 0
	s_nop 0
	s_nop 0
	s_nop 0
	s_nop 0
	s_nop 0
	v_readlane_b32 s6, v254, 10
	s_waitcnt lgkmcnt(0)
	v_mov_b32_e32 v0, 0
	v_readlane_b32 s7, v254, 11
	s_nop 4
	global_load_dword v2, v0, s[6:7] sc1
	s_waitcnt vmcnt(0)
	v_cmp_eq_u32_e32 vcc, v2, v1
	s_and_saveexec_b64 s[6:7], vcc
	s_cbranch_execz .LBB0_355
	s_mov_b32 s2, 1
	s_mov_b64 s[8:9], 0
	s_branch .LBB0_346

; DI unsigned xb_ld(unsigned* p)              { return __hip_atomic_load(p, __ATOMIC_RELAXED, __HIP_MEMORY_SCOPE_AGENT); }
; DI unsigned xb_add(unsigned* p, unsigned v) { return __hip_atomic_fetch_add(p, v, __ATOMIC_RELAXED, __HIP_MEMORY_SCOPE_AGENT); }
; #define XB_SPIN(cond, bar) do { unsigned _sp = 0; while (cond) { __builtin_amdgcn_s_sleep(1); \
;     if ((++_sp & 255u) == 0u) { if (xb_ld(&(bar)[XB_TMO])) break; if (_sp > XB_SPIN_CAP) { atomicAdd(&(bar)[XB_TMO], 1u); break; } } } } while (0)
; DI void xcd_barrier(const XcdBarrier& b, int tid) {
;     ...
;         const unsigned old = xb_add(&bar[XB_XSUB(b.x)], 1u);
;         const unsigned gen = old / nloc;
;         if (old + 1u == (gen + 1u) * nloc) {
;             __builtin_amdgcn_fence(__ATOMIC_RELEASE, "agent");
;             asm volatile("s_waitcnt vmcnt(0)" ::: "memory");
;             const unsigned og = xb_add(&bar[XB_TOP], 1u);
;             const unsigned tg = og / nx;
;             if (og + 1u == (tg + 1u) * nx) xb_add(&bar[XB_TOPGEN], 1u);
;             else XB_SPIN(xb_ld(&bar[XB_TOPGEN]) == tg, bar);
;             __builtin_amdgcn_fence(__ATOMIC_ACQUIRE, "agent");
;             xb_add(&bar[XB_XGEN(b.x)], 1u);
;             asm volatile("s_waitcnt vmcnt(0)" ::: "memory");
;         } else {
;             XB_SPIN(xb_ld(&bar[XB_XGEN(b.x)]) == gen, bar);
.LBB0_1663:
	s_or_b64 exec, exec, s[6:7]
	v_cvt_f32_u32_e32 v4, v2
	s_waitcnt vmcnt(0)
	v_readfirstlane_b32 s2, v3
	v_sub_u32_e32 v3, 0, v2
	v_rcp_iflag_f32_e32 v4, v4
	v_add_u32_e32 v5, s2, v1
	v_mul_f32_e32 v4, 0x4f7ffffe, v4
	v_cvt_u32_f32_e32 v4, v4
	v_mul_lo_u32 v1, v3, v4
	v_mul_hi_u32 v1, v4, v1
	v_add_u32_e32 v1, v4, v1
	v_mul_hi_u32 v1, v5, v1
	v_mul_lo_u32 v3, v1, v2
	v_sub_u32_e32 v3, v5, v3
	v_add_u32_e32 v4, 1, v1
	v_cmp_ge_u32_e32 vcc, v3, v2
	s_nop 1
	v_cndmask_b32_e32 v1, v1, v4, vcc
	v_sub_u32_e32 v4, v3, v2
	v_cndmask_b32_e32 v3, v3, v4, vcc
	v_add_u32_e32 v4, 1, v1
	v_cmp_ge_u32_e32 vcc, v3, v2
	v_add_u32_e32 v3, 1, v5
	s_nop 0
	v_cndmask_b32_e32 v1, v1, v4, vcc
	v_mul_lo_u32 v4, v2, v1
	v_add_u32_e32 v2, v4, v2
	v_cmp_ne_u32_e32 vcc, v3, v2
	s_and_saveexec_b64 s[2:3], vcc
	s_xor_b64 s[6:7], exec, s[2:3]
	s_cbranch_execz .LBB0_1677
	v_sub_u32_e32 v4, v2, v4
	v_lshrrev_b32_e32 v4, 1, v4
	v_sub_u32_e32 v4, v2, v4
	v_cmp_eq_u32_e32 vcc, v3, v4
	s_cbranch_vccz .Lbarwb_skip_11
	buffer_wbl2 sc1
.Lbarwb_skip_11:
	s_nop 0
	s_nop 0
	s_nop 0
	s_nop 0
	s_nop 0
	s_nop 0
	s_nop 0
	s_nop 0
	s_nop 0
	v_readlane_b32 s2, v254, 10
	s_waitcnt lgkmcnt(0)
	v_mov_b32_e32 v0, 0
	v_readlane_b32 s3, v254, 11
	s_nop 4
	global_load_dword v2, v0, s[2:3] sc1
	s_waitcnt vmcnt(0)
	v_cmp_eq_u32_e32 vcc, v2, v1
	s_and_saveexec_b64 s[8:9], vcc
	s_cbranch_execz .LBB0_1676
	s_mov_b32 s2, 1
	s_mov_b64 s[10:11], 0
	s_branch .LBB0_1667

; DI unsigned xb_ld(unsigned* p)              { return __hip_atomic_load(p, __ATOMIC_RELAXED, __HIP_MEMORY_SCOPE_AGENT); }
; DI unsigned xb_add(unsigned* p, unsigned v) { return __hip_atomic_fetch_add(p, v, __ATOMIC_RELAXED, __HIP_MEMORY_SCOPE_AGENT); }
; #define XB_SPIN(cond, bar) do { unsigned _sp = 0; while (cond) { __builtin_amdgcn_s_sleep(1); \
;     if ((++_sp & 255u) == 0u) { if (xb_ld(&(bar)[XB_TMO])) break; if (_sp > XB_SPIN_CAP) { atomicAdd(&(bar)[XB_TMO], 1u); break; } } } } while (0)
; DI void xcd_barrier(const XcdBarrier& b, int tid) {
;     ...
;         const unsigned old = xb_add(&bar[XB_XSUB(b.x)], 1u);
;         const unsigned gen = old / nloc;
;         if (old + 1u == (gen + 1u) * nloc) {
;             __builtin_amdgcn_fence(__ATOMIC_RELEASE, "agent");
;             asm volatile("s_waitcnt vmcnt(0)" ::: "memory");
;             const unsigned og = xb_add(&bar[XB_TOP], 1u);
;             const unsigned tg = og / nx;
;             if (og + 1u == (tg + 1u) * nx) xb_add(&bar[XB_TOPGEN], 1u);
;             else XB_SPIN(xb_ld(&bar[XB_TOPGEN]) == tg, bar);
;             __builtin_amdgcn_fence(__ATOMIC_ACQUIRE, "agent");
;             xb_add(&bar[XB_XGEN(b.x)], 1u);
;             asm volatile("s_waitcnt vmcnt(0)" ::: "memory");
;         } else {
;             XB_SPIN(xb_ld(&bar[XB_XGEN(b.x)]) == gen, bar);
.LBB0_1731:
	s_or_b64 exec, exec, s[4:5]
	v_cvt_f32_u32_e32 v4, v2
	s_waitcnt vmcnt(0)
	v_readfirstlane_b32 s3, v3
	v_sub_u32_e32 v3, 0, v2
	v_rcp_iflag_f32_e32 v4, v4
	v_add_u32_e32 v5, s3, v1
	v_mul_f32_e32 v4, 0x4f7ffffe, v4
	v_cvt_u32_f32_e32 v4, v4
	v_mul_lo_u32 v1, v3, v4
	v_mul_hi_u32 v1, v4, v1
	v_add_u32_e32 v1, v4, v1
	v_mul_hi_u32 v1, v5, v1
	v_mul_lo_u32 v3, v1, v2
	v_sub_u32_e32 v3, v5, v3
	v_add_u32_e32 v4, 1, v1
	v_cmp_ge_u32_e32 vcc, v3, v2
	s_nop 1
	v_cndmask_b32_e32 v1, v1, v4, vcc
	v_sub_u32_e32 v4, v3, v2
	v_cndmask_b32_e32 v3, v3, v4, vcc
	v_add_u32_e32 v4, 1, v1
	v_cmp_ge_u32_e32 vcc, v3, v2
	v_add_u32_e32 v3, 1, v5
	s_nop 0
	v_cndmask_b32_e32 v1, v1, v4, vcc
	v_mul_lo_u32 v4, v2, v1
	v_add_u32_e32 v2, v4, v2
	v_cmp_ne_u32_e32 vcc, v3, v2
	s_and_saveexec_b64 s[4:5], vcc
	s_xor_b64 s[4:5], exec, s[4:5]
	s_cbranch_execz .LBB0_1745
	v_sub_u32_e32 v4, v2, v4
	v_lshrrev_b32_e32 v4, 1, v4
	v_sub_u32_e32 v4, v2, v4
	v_cmp_eq_u32_e32 vcc, v3, v4
	s_cbranch_vccz .Lbarwb_skip_12
	buffer_wbl2 sc1
.Lbarwb_skip_12:
	s_nop 0
	s_nop 0
	s_nop 0
	s_nop 0
	s_nop 0
	s_nop 0
	s_nop 0
	s_nop 0
	s_nop 0
	v_readlane_b32 s6, v254, 10
	s_waitcnt lgkmcnt(0)
	v_mov_b32_e32 v0, 0
	v_readlane_b32 s7, v254, 11
	s_nop 4
	global_load_dword v2, v0, s[6:7] sc1
	s_waitcnt vmcnt(0)
	v_cmp_eq_u32_e32 vcc, v2, v1
	s_and_saveexec_b64 s[6:7], vcc
	s_cbranch_execz .LBB0_1744
	s_mov_b32 s3, 1
	s_mov_b64 s[8:9], 0
	s_branch .LBB0_1735
